# v43 + waves 0-3 (the leading half) hold s_setprio 1 through the FFN-in epilogue, waves 4-7 get it back at the loop preheader
# baseline (speedup 1.0000x reference)
; #define PG8_STAGE(bufoff, gbase, voff) do { _Pragma("unroll") for (int _i = 0; _i < 2; ++_i) \
;         __builtin_amdgcn_global_load_lds((const unsigned*)((const char*)(gbase) + (voff)[_i]), (LAS unsigned*)(lds + (bufoff) + ldsw + _i * 8192), 16, 0, 0); } while (0)
; #define PG8_LDA(dst, b, h) do { _Pragma("unroll") for (int m = 0; m < 4; ++m) _Pragma("unroll") for (int k = 0; k < 2; ++k) dst[m][k] = *(const LAS bf16x8*)(lds + PG8_SA(b, h) + aoff + m * 2048 + k * 1024); } while (0)
; #define PG8_LDB(dst, b, h) do { _Pragma("unroll") for (int n = 0; n < 2; ++n) _Pragma("unroll") for (int k = 0; k < 2; ++k) dst[n][k] = *(const LAS bf16x8*)(lds + PG8_SB(b, h) + boff + n * 2048 + k * 1024); } while (0)
; #define PG8_MMA(ai, bj, At, Bt) do { __builtin_amdgcn_s_setprio(1); _Pragma("unroll") for (int m = 0; m < 4; ++m) _Pragma("unroll") for (int n = 0; n < 2; ++n) _Pragma("unroll") for (int k = 0; k < 2; ++k) \
;         acc[ai][bj][m][n] = __builtin_amdgcn_mfma_f32_16x16x32_bf16(Bt[n][k], At[m][k], acc[ai][bj][m][n], 0, 0, 0); __builtin_amdgcn_s_setprio(0); } while (0)
; #define PG8_WAIT_V(n) asm volatile("s_waitcnt vmcnt(" #n ")" ::: "memory")
; #define PG8_WAIT_L(n) asm volatile("s_waitcnt lgkmcnt(" #n ")" ::: "memory")
; #define PG8_BAR __builtin_amdgcn_s_barrier()
; #define PG8_SCHED __builtin_amdgcn_sched_barrier(0)
; template <class Epi, class Sched>
; __device__ __forceinline__ void gemm_phase(LAS unsigned char* lds, const Gemm g, const Sched& S, const Epi& E) {
;     ...
;             PG8_LDB(B0, 0, 0); PG8_LDB(B1, 0, 1); PG8_SCHED; PG8_LDA(At, 0, 0); PG8_STAGE(PG8_SA(1, 1), a1 + hsA, voffA);
;             PG8_WAIT_V(8); PG8_WAIT_L(0); PG8_BAR; PG8_MMA(0, 0, At, B0); PG8_MMA(0, 1, At, B1); PG8_BAR; PG8_SCHED;
;     ...
; #pragma unroll
;         for (int a = 0; a < 2; ++a)
; #pragma unroll
;             for (int b = 0; b < 2; ++b)
; #pragma unroll
;                 for (int m = 0; m < 4; ++m)
; #pragma unroll
;                     for (int n = 0; n < 2; ++n) acc[a][b][m][n] = (f32x4){0.f, 0.f, 0.f, 0.f};
.LBB0_220:
	s_add_u32 s50, s2, s46
	s_addc_u32 s51, s3, s47
	s_add_u32 s76, s7, s48
	s_addc_u32 s77, s11, s49
	s_andn2_b64 vcc, exec, s[74:75]
	s_cbranch_vccnz .Lzc_6242
	s_and_b64 s[8:9], s[36:37], exec
	s_cselect_b32 s10, s51, s1
	s_cselect_b32 s43, s50, s0
	s_cselect_b32 s45, s77, s39
	s_cselect_b32 vcc_lo, s76, s38
	s_add_u32 s0, s0, 0x40080
	s_addc_u32 s1, s1, 0
	s_add_u32 vcc_hi, s38, 0x100
	v_mov_b32_e32 v6, 0
	s_mov_b64 s[22:23], s[74:75]
	s_addc_u32 s8, s39, 0
	s_mov_b32 s9, 0
	v_mov_b32_e32 v7, v6
	v_mov_b32_e32 v8, v6
	v_mov_b32_e32 v9, v6
	v_mov_b32_e32 v14, v6
	v_mov_b32_e32 v15, v6
	v_mov_b32_e32 v16, v6
	v_mov_b32_e32 v17, v6
	v_mov_b32_e32 v22, v6
	v_mov_b32_e32 v23, v6
	v_mov_b32_e32 v24, v6
	v_mov_b32_e32 v25, v6
	v_mov_b32_e32 v30, v6
	v_mov_b32_e32 v31, v6
	v_mov_b32_e32 v32, v6
	v_mov_b32_e32 v33, v6
	v_mov_b32_e32 v38, v6
	v_mov_b32_e32 v39, v6
	v_mov_b32_e32 v40, v6
	v_mov_b32_e32 v41, v6
	v_mov_b32_e32 v46, v6
	v_mov_b32_e32 v47, v6
	v_mov_b32_e32 v48, v6
	v_mov_b32_e32 v49, v6
	v_mov_b32_e32 v54, v6
	v_mov_b32_e32 v55, v6
	v_mov_b32_e32 v56, v6
	v_mov_b32_e32 v57, v6
	v_mov_b32_e32 v62, v6
	v_mov_b32_e32 v63, v6
	v_mov_b32_e32 v64, v6
	v_mov_b32_e32 v65, v6
	v_mov_b32_e32 v2, v6
	v_mov_b32_e32 v3, v6
	v_mov_b32_e32 v4, v6
	v_mov_b32_e32 v5, v6
	v_mov_b32_e32 v10, v6
	v_mov_b32_e32 v11, v6
	v_mov_b32_e32 v12, v6
	v_mov_b32_e32 v13, v6
	v_mov_b32_e32 v18, v6
	v_mov_b32_e32 v19, v6
	v_mov_b32_e32 v20, v6
	v_mov_b32_e32 v21, v6
	v_mov_b32_e32 v26, v6
	v_mov_b32_e32 v27, v6
	v_mov_b32_e32 v28, v6
	v_mov_b32_e32 v29, v6
	v_mov_b32_e32 v34, v6
	v_mov_b32_e32 v35, v6
	v_mov_b32_e32 v36, v6
	v_mov_b32_e32 v37, v6
	v_mov_b32_e32 v42, v6
	v_mov_b32_e32 v43, v6
	v_mov_b32_e32 v44, v6
	v_mov_b32_e32 v45, v6
	v_mov_b32_e32 v50, v6
	v_mov_b32_e32 v51, v6
	v_mov_b32_e32 v52, v6
	v_mov_b32_e32 v53, v6
	v_mov_b32_e32 v58, v6
	v_mov_b32_e32 v59, v6
	v_mov_b32_e32 v60, v6
	v_mov_b32_e32 v61, v6
	v_mov_b32_e32 v70, v6
	v_mov_b32_e32 v71, v6
	v_mov_b32_e32 v72, v6
	v_mov_b32_e32 v73, v6
	v_mov_b32_e32 v78, v6
	v_mov_b32_e32 v79, v6
	v_mov_b32_e32 v80, v6
	v_mov_b32_e32 v81, v6
	v_mov_b32_e32 v86, v6
	v_mov_b32_e32 v87, v6
	v_mov_b32_e32 v88, v6
	v_mov_b32_e32 v89, v6
	v_mov_b32_e32 v94, v6
	v_mov_b32_e32 v95, v6
	v_mov_b32_e32 v96, v6
	v_mov_b32_e32 v97, v6
	v_mov_b32_e32 v102, v6
	v_mov_b32_e32 v103, v6
	v_mov_b32_e32 v104, v6
	v_mov_b32_e32 v105, v6
	v_mov_b32_e32 v110, v6
	v_mov_b32_e32 v111, v6
	v_mov_b32_e32 v112, v6
	v_mov_b32_e32 v113, v6
	v_mov_b32_e32 v118, v6
	v_mov_b32_e32 v119, v6
	v_mov_b32_e32 v120, v6
	v_mov_b32_e32 v121, v6
	v_mov_b32_e32 v126, v6
	v_mov_b32_e32 v127, v6
	v_mov_b32_e32 v128, v6
	v_mov_b32_e32 v129, v6
	v_mov_b32_e32 v66, v6
	v_mov_b32_e32 v67, v6
	v_mov_b32_e32 v68, v6
	v_mov_b32_e32 v69, v6
	v_mov_b32_e32 v74, v6
	v_mov_b32_e32 v75, v6
	v_mov_b32_e32 v76, v6
	v_mov_b32_e32 v77, v6
	v_mov_b32_e32 v82, v6
	v_mov_b32_e32 v83, v6
	v_mov_b32_e32 v84, v6
	v_mov_b32_e32 v85, v6
	v_mov_b32_e32 v90, v6
	v_mov_b32_e32 v91, v6
	v_mov_b32_e32 v92, v6
	v_mov_b32_e32 v93, v6
	v_mov_b32_e32 v98, v6
	v_mov_b32_e32 v99, v6
	v_mov_b32_e32 v100, v6
	v_mov_b32_e32 v101, v6
	v_mov_b32_e32 v106, v6
	v_mov_b32_e32 v107, v6
	v_mov_b32_e32 v108, v6
	v_mov_b32_e32 v109, v6
	v_mov_b32_e32 v114, v6
	v_mov_b32_e32 v115, v6
	v_mov_b32_e32 v116, v6
	v_mov_b32_e32 v117, v6
	v_mov_b32_e32 v122, v6
	v_mov_b32_e32 v123, v6
	v_mov_b32_e32 v124, v6
	v_mov_b32_e32 v125, v6
	v_readfirstlane_b32 s96, v193
	s_lshr_b32 s96, s96, 8
	s_cmp_eq_u32 s96, 1
	s_cbranch_scc0 .Lnp0_222
	s_setprio 1
	s_branch .Lnp_222
.Lnp0_222:
	s_setprio 0
.Lnp_222:
.LBB0_222:
	s_add_i32 s96, s9, 2
	s_add_u32 s20, s0, 0xfffc0080
	s_addc_u32 s21, s1, -1
	s_add_i32 s74, 0, 0x10000
	s_cmp_eq_u32 s82, s9
	s_cselect_b32 s85, s10, s21
	s_cselect_b32 s84, s43, s20
	s_cselect_b32 s39, s45, s8
	s_cselect_b32 s38, vcc_lo, vcc_hi
	s_add_i32 s9, 0, 0x14000
	v_add_u32_e32 v154, s74, v160
	v_add_u32_e32 v174, s9, v160
	ds_read_b128 v[142:145], v154
	ds_read_b128 v[146:149], v154 offset:1024
	ds_read_b128 v[150:153], v154 offset:2048
	ds_read_b128 v[154:157], v154 offset:3072
	ds_read_b128 v[162:165], v174
	ds_read_b128 v[166:169], v174 offset:1024
	ds_read_b128 v[170:173], v174 offset:2048
	ds_read_b128 v[174:177], v174 offset:3072
	s_add_i32 m0, s16, 0xc000
	ds_read_b128 v[178:181], v161
	ds_read_b128 v[182:185], v161 offset:1024
	ds_read_b128 v[186:189], v161 offset:2048
	ds_read_b128 v[208:211], v161 offset:3072
	ds_read_b128 v[212:215], v161 offset:4096
	ds_read_b128 v[216:219], v161 offset:5120
	ds_read_b128 v[220:223], v161 offset:6144
	ds_read_b128 v[224:227], v161 offset:7168
	global_load_lds_dwordx4 v138, s[0:1]
	s_add_i32 m0, s16, 0xe000
	s_nop 0
	global_load_lds_dwordx4 v140, s[0:1]
	s_waitcnt vmcnt(8)
	s_waitcnt lgkmcnt(0)
	s_barrier
; #define PG8_STAGE(bufoff, gbase, voff) do { _Pragma("unroll") for (int _i = 0; _i < 2; ++_i) \
;         __builtin_amdgcn_global_load_lds((const unsigned*)((const char*)(gbase) + (voff)[_i]), (LAS unsigned*)(lds + (bufoff) + ldsw + _i * 8192), 16, 0, 0); } while (0)
; #define PG8_LDA(dst, b, h) do { _Pragma("unroll") for (int m = 0; m < 4; ++m) _Pragma("unroll") for (int k = 0; k < 2; ++k) dst[m][k] = *(const LAS bf16x8*)(lds + PG8_SA(b, h) + aoff + m * 2048 + k * 1024); } while (0)
; #define PG8_LDB(dst, b, h) do { _Pragma("unroll") for (int n = 0; n < 2; ++n) _Pragma("unroll") for (int k = 0; k < 2; ++k) dst[n][k] = *(const LAS bf16x8*)(lds + PG8_SB(b, h) + boff + n * 2048 + k * 1024); } while (0)
; #define PG8_MMA(ai, bj, At, Bt) do { __builtin_amdgcn_s_setprio(1); _Pragma("unroll") for (int m = 0; m < 4; ++m) _Pragma("unroll") for (int n = 0; n < 2; ++n) _Pragma("unroll") for (int k = 0; k < 2; ++k) \
;         acc[ai][bj][m][n] = __builtin_amdgcn_mfma_f32_16x16x32_bf16(Bt[n][k], At[m][k], acc[ai][bj][m][n], 0, 0, 0); __builtin_amdgcn_s_setprio(0); } while (0)
; #define PG8_WAIT_V(n) asm volatile("s_waitcnt vmcnt(" #n ")" ::: "memory")
; #define PG8_WAIT_L(n) asm volatile("s_waitcnt lgkmcnt(" #n ")" ::: "memory")
; #define PG8_BAR __builtin_amdgcn_s_barrier()
; #define PG8_SCHED __builtin_amdgcn_sched_barrier(0)
; template <class Epi, class Sched>
; __device__ __forceinline__ void gemm_phase(LAS unsigned char* lds, const Gemm g, const Sched& S, const Epi& E) {
;     ...
;             PG8_WAIT_V(8); PG8_WAIT_L(0); PG8_BAR; PG8_MMA(0, 0, At, B0); PG8_MMA(0, 1, At, B1); PG8_BAR; PG8_SCHED;
;             PG8_LDA(At, 0, 1); PG8_STAGE(PG8_SB(0, 0), b2, voffB); PG8_STAGE(PG8_SB(0, 1), b2 + hsB, voffB); PG8_STAGE(PG8_SA(0, 0), a2, voffA);
;             PG8_WAIT_V(8); PG8_WAIT_L(0); PG8_BAR; PG8_MMA(1, 0, At, B0); PG8_MMA(1, 1, At, B1); PG8_BAR; PG8_SCHED;
;             PG8_LDB(B0, 1, 0); PG8_LDB(B1, 1, 1); PG8_SCHED; PG8_LDA(At, 1, 0); PG8_STAGE(PG8_SA(0, 1), a2 + hsA, voffA);
;             PG8_WAIT_V(8); PG8_WAIT_L(0); PG8_BAR; PG8_MMA(0, 0, At, B0); PG8_MMA(0, 1, At, B1); PG8_BAR; PG8_SCHED;
	s_waitcnt lgkmcnt(0)
	v_mfma_f32_16x16x32_bf16 v[122:125], v[142:145], v[178:181], v[122:125]
	v_mfma_f32_16x16x32_bf16 v[114:117], v[150:153], v[178:181], v[114:117]
	v_mfma_f32_16x16x32_bf16 v[106:109], v[142:145], v[186:189], v[106:109]
	v_mfma_f32_16x16x32_bf16 v[98:101], v[150:153], v[186:189], v[98:101]
	v_mfma_f32_16x16x32_bf16 v[90:93], v[142:145], v[212:215], v[90:93]
	v_mfma_f32_16x16x32_bf16 v[82:85], v[150:153], v[212:215], v[82:85]
	v_mfma_f32_16x16x32_bf16 v[74:77], v[142:145], v[220:223], v[74:77]
	v_mfma_f32_16x16x32_bf16 v[66:69], v[150:153], v[220:223], v[66:69]
	v_mfma_f32_16x16x32_bf16 v[122:125], v[146:149], v[182:185], v[122:125]
	v_mfma_f32_16x16x32_bf16 v[114:117], v[154:157], v[182:185], v[114:117]
	v_mfma_f32_16x16x32_bf16 v[106:109], v[146:149], v[208:211], v[106:109]
	v_mfma_f32_16x16x32_bf16 v[98:101], v[154:157], v[208:211], v[98:101]
	v_mfma_f32_16x16x32_bf16 v[90:93], v[146:149], v[216:219], v[90:93]
	v_mfma_f32_16x16x32_bf16 v[82:85], v[154:157], v[216:219], v[82:85]
	v_mfma_f32_16x16x32_bf16 v[74:77], v[146:149], v[224:227], v[74:77]
	v_mfma_f32_16x16x32_bf16 v[66:69], v[154:157], v[224:227], v[66:69]
	v_mfma_f32_16x16x32_bf16 v[126:129], v[162:165], v[178:181], v[126:129]
	v_mfma_f32_16x16x32_bf16 v[118:121], v[170:173], v[178:181], v[118:121]
	v_mfma_f32_16x16x32_bf16 v[110:113], v[162:165], v[186:189], v[110:113]
	v_mfma_f32_16x16x32_bf16 v[102:105], v[170:173], v[186:189], v[102:105]
	v_mfma_f32_16x16x32_bf16 v[94:97], v[162:165], v[212:215], v[94:97]
	v_mfma_f32_16x16x32_bf16 v[86:89], v[170:173], v[212:215], v[86:89]
	v_mfma_f32_16x16x32_bf16 v[78:81], v[162:165], v[220:223], v[78:81]
	v_mfma_f32_16x16x32_bf16 v[70:73], v[170:173], v[220:223], v[70:73]
	v_mfma_f32_16x16x32_bf16 v[126:129], v[166:169], v[182:185], v[126:129]
	v_mfma_f32_16x16x32_bf16 v[118:121], v[174:177], v[182:185], v[118:121]
	v_mfma_f32_16x16x32_bf16 v[110:113], v[166:169], v[208:211], v[110:113]
	v_mfma_f32_16x16x32_bf16 v[102:105], v[174:177], v[208:211], v[102:105]
	v_mfma_f32_16x16x32_bf16 v[94:97], v[166:169], v[216:219], v[94:97]
	v_mfma_f32_16x16x32_bf16 v[86:89], v[174:177], v[216:219], v[86:89]
	v_mfma_f32_16x16x32_bf16 v[78:81], v[166:169], v[224:227], v[78:81]
	v_mfma_f32_16x16x32_bf16 v[70:73], v[174:177], v[224:227], v[70:73]
	s_barrier
	s_add_i32 s20, s74, s12
	s_mov_b32 m0, s20
	ds_read_b128 v[178:181], v161 offset:16384
	ds_read_b128 v[182:185], v161 offset:17408
	ds_read_b128 v[186:189], v161 offset:18432
	ds_read_b128 v[208:211], v161 offset:19456
	ds_read_b128 v[212:215], v161 offset:20480
	ds_read_b128 v[216:219], v161 offset:21504
	ds_read_b128 v[220:223], v161 offset:22528
	ds_read_b128 v[224:227], v161 offset:23552
	global_load_lds_dwordx4 v0, s[38:39]
	s_add_i32 m0, s20, 0x2000
	s_add_u32 s20, s38, 0x40000
	s_addc_u32 s21, s39, 0
	s_add_i32 s9, s9, s12
	global_load_lds_dwordx4 v130, s[38:39]
	s_mov_b32 m0, s9
	s_nop 0
	global_load_lds_dwordx4 v0, s[20:21]
	s_add_i32 m0, s9, 0x2000
	s_nop 0
	global_load_lds_dwordx4 v130, s[20:21]
	s_mov_b32 m0, s16
	s_nop 0
	global_load_lds_dwordx4 v134, s[84:85]
	s_mov_b32 m0, s30
	s_nop 0
	global_load_lds_dwordx4 v132, s[84:85]
	s_waitcnt vmcnt(8)
	s_waitcnt lgkmcnt(0)
	s_barrier
	s_waitcnt lgkmcnt(0)
	v_mfma_f32_16x16x32_bf16 v[58:61], v[142:145], v[178:181], v[58:61]
	v_mfma_f32_16x16x32_bf16 v[50:53], v[150:153], v[178:181], v[50:53]
	v_mfma_f32_16x16x32_bf16 v[42:45], v[142:145], v[186:189], v[42:45]
	v_mfma_f32_16x16x32_bf16 v[34:37], v[150:153], v[186:189], v[34:37]
	v_mfma_f32_16x16x32_bf16 v[26:29], v[142:145], v[212:215], v[26:29]
	v_mfma_f32_16x16x32_bf16 v[18:21], v[150:153], v[212:215], v[18:21]
	v_mfma_f32_16x16x32_bf16 v[10:13], v[142:145], v[220:223], v[10:13]
	v_mfma_f32_16x16x32_bf16 v[2:5], v[150:153], v[220:223], v[2:5]
	v_mfma_f32_16x16x32_bf16 v[58:61], v[146:149], v[182:185], v[58:61]
	v_mfma_f32_16x16x32_bf16 v[50:53], v[154:157], v[182:185], v[50:53]
	v_mfma_f32_16x16x32_bf16 v[42:45], v[146:149], v[208:211], v[42:45]
	v_mfma_f32_16x16x32_bf16 v[34:37], v[154:157], v[208:211], v[34:37]
	v_mfma_f32_16x16x32_bf16 v[26:29], v[146:149], v[216:219], v[26:29]
	v_mfma_f32_16x16x32_bf16 v[18:21], v[154:157], v[216:219], v[18:21]
	v_mfma_f32_16x16x32_bf16 v[10:13], v[146:149], v[224:227], v[10:13]
	v_mfma_f32_16x16x32_bf16 v[2:5], v[154:157], v[224:227], v[2:5]
	v_mfma_f32_16x16x32_bf16 v[62:65], v[162:165], v[178:181], v[62:65]
	v_mfma_f32_16x16x32_bf16 v[54:57], v[170:173], v[178:181], v[54:57]
	v_mfma_f32_16x16x32_bf16 v[46:49], v[162:165], v[186:189], v[46:49]
	v_mfma_f32_16x16x32_bf16 v[38:41], v[170:173], v[186:189], v[38:41]
	v_mfma_f32_16x16x32_bf16 v[30:33], v[162:165], v[212:215], v[30:33]
	v_mfma_f32_16x16x32_bf16 v[22:25], v[170:173], v[212:215], v[22:25]
	v_mfma_f32_16x16x32_bf16 v[14:17], v[162:165], v[220:223], v[14:17]
	v_mfma_f32_16x16x32_bf16 v[6:9], v[170:173], v[220:223], v[6:9]
	v_mfma_f32_16x16x32_bf16 v[62:65], v[166:169], v[182:185], v[62:65]
	v_mfma_f32_16x16x32_bf16 v[54:57], v[174:177], v[182:185], v[54:57]
	v_mfma_f32_16x16x32_bf16 v[46:49], v[166:169], v[208:211], v[46:49]
	v_mfma_f32_16x16x32_bf16 v[38:41], v[174:177], v[208:211], v[38:41]
	v_mfma_f32_16x16x32_bf16 v[30:33], v[166:169], v[216:219], v[30:33]
	v_mfma_f32_16x16x32_bf16 v[22:25], v[174:177], v[216:219], v[22:25]
	v_mfma_f32_16x16x32_bf16 v[14:17], v[166:169], v[224:227], v[14:17]
	v_mfma_f32_16x16x32_bf16 v[6:9], v[174:177], v[224:227], v[6:9]
	s_barrier
; #define PG8_STAGE(bufoff, gbase, voff) do { _Pragma("unroll") for (int _i = 0; _i < 2; ++_i) \
;         __builtin_amdgcn_global_load_lds((const unsigned*)((const char*)(gbase) + (voff)[_i]), (LAS unsigned*)(lds + (bufoff) + ldsw + _i * 8192), 16, 0, 0); } while (0)
; #define PG8_LDA(dst, b, h) do { _Pragma("unroll") for (int m = 0; m < 4; ++m) _Pragma("unroll") for (int k = 0; k < 2; ++k) dst[m][k] = *(const LAS bf16x8*)(lds + PG8_SA(b, h) + aoff + m * 2048 + k * 1024); } while (0)
; #define PG8_LDB(dst, b, h) do { _Pragma("unroll") for (int n = 0; n < 2; ++n) _Pragma("unroll") for (int k = 0; k < 2; ++k) dst[n][k] = *(const LAS bf16x8*)(lds + PG8_SB(b, h) + boff + n * 2048 + k * 1024); } while (0)
; #define PG8_MMA(ai, bj, At, Bt) do { __builtin_amdgcn_s_setprio(1); _Pragma("unroll") for (int m = 0; m < 4; ++m) _Pragma("unroll") for (int n = 0; n < 2; ++n) _Pragma("unroll") for (int k = 0; k < 2; ++k) \
;         acc[ai][bj][m][n] = __builtin_amdgcn_mfma_f32_16x16x32_bf16(Bt[n][k], At[m][k], acc[ai][bj][m][n], 0, 0, 0); __builtin_amdgcn_s_setprio(0); } while (0)
; #define PG8_WAIT_V(n) asm volatile("s_waitcnt vmcnt(" #n ")" ::: "memory")
; #define PG8_WAIT_L(n) asm volatile("s_waitcnt lgkmcnt(" #n ")" ::: "memory")
; #define PG8_BAR __builtin_amdgcn_s_barrier()
; #define PG8_SCHED __builtin_amdgcn_sched_barrier(0)
; template <class Epi, class Sched>
; __device__ __forceinline__ void gemm_phase(LAS unsigned char* lds, const Gemm g, const Sched& S, const Epi& E) {
;     ...
;             PG8_LDB(B0, 1, 0); PG8_LDB(B1, 1, 1); PG8_SCHED; PG8_LDA(At, 1, 0); PG8_STAGE(PG8_SA(0, 1), a2 + hsA, voffA);
;             PG8_WAIT_V(8); PG8_WAIT_L(0); PG8_BAR; PG8_MMA(0, 0, At, B0); PG8_MMA(0, 1, At, B1); PG8_BAR; PG8_SCHED;
;             PG8_LDA(At, 1, 1); PG8_STAGE(PG8_SB(1, 0), b3, voffB); PG8_STAGE(PG8_SB(1, 1), b3 + hsB, voffB); PG8_STAGE(PG8_SA(1, 0), a3, voffA);
;             PG8_WAIT_V(8); PG8_WAIT_L(0); PG8_BAR; PG8_MMA(1, 0, At, B0); PG8_MMA(1, 1, At, B1); PG8_BAR; PG8_SCHED;
;         }
;         if (wr == 0) PG8_BAR;
	s_add_i32 s9, 0, 0x18000
	s_add_i32 s74, 0, 0x1c000
	v_add_u32_e32 v154, s9, v160
	v_add_u32_e32 v174, s74, v160
	ds_read_b128 v[142:145], v154
	ds_read_b128 v[146:149], v154 offset:1024
	ds_read_b128 v[150:153], v154 offset:2048
	ds_read_b128 v[154:157], v154 offset:3072
	ds_read_b128 v[162:165], v174
	ds_read_b128 v[166:169], v174 offset:1024
	ds_read_b128 v[170:173], v174 offset:2048
	ds_read_b128 v[174:177], v174 offset:3072
	s_add_u32 s20, s84, 0x40000
	s_addc_u32 s21, s85, 0
	s_mov_b32 m0, s52
	ds_read_b128 v[178:181], v161 offset:32768
	ds_read_b128 v[182:185], v161 offset:33792
	ds_read_b128 v[186:189], v161 offset:34816
	ds_read_b128 v[208:211], v161 offset:35840
	ds_read_b128 v[212:215], v161 offset:36864
	ds_read_b128 v[216:219], v161 offset:37888
	ds_read_b128 v[220:223], v161 offset:38912
	ds_read_b128 v[224:227], v161 offset:39936
	global_load_lds_dwordx4 v134, s[20:21]
	s_mov_b32 m0, s56
	s_nop 0
	global_load_lds_dwordx4 v132, s[20:21]
	s_waitcnt vmcnt(8)
	s_waitcnt lgkmcnt(0)
	s_barrier
	s_waitcnt lgkmcnt(0)
	v_mfma_f32_16x16x32_bf16 v[122:125], v[142:145], v[178:181], v[122:125]
	v_mfma_f32_16x16x32_bf16 v[114:117], v[150:153], v[178:181], v[114:117]
	v_mfma_f32_16x16x32_bf16 v[106:109], v[142:145], v[186:189], v[106:109]
	v_mfma_f32_16x16x32_bf16 v[98:101], v[150:153], v[186:189], v[98:101]
	v_mfma_f32_16x16x32_bf16 v[90:93], v[142:145], v[212:215], v[90:93]
	v_mfma_f32_16x16x32_bf16 v[82:85], v[150:153], v[212:215], v[82:85]
	v_mfma_f32_16x16x32_bf16 v[74:77], v[142:145], v[220:223], v[74:77]
	v_mfma_f32_16x16x32_bf16 v[66:69], v[150:153], v[220:223], v[66:69]
	v_mfma_f32_16x16x32_bf16 v[122:125], v[146:149], v[182:185], v[122:125]
	v_mfma_f32_16x16x32_bf16 v[114:117], v[154:157], v[182:185], v[114:117]
	v_mfma_f32_16x16x32_bf16 v[106:109], v[146:149], v[208:211], v[106:109]
	v_mfma_f32_16x16x32_bf16 v[98:101], v[154:157], v[208:211], v[98:101]
	v_mfma_f32_16x16x32_bf16 v[90:93], v[146:149], v[216:219], v[90:93]
	v_mfma_f32_16x16x32_bf16 v[82:85], v[154:157], v[216:219], v[82:85]
	v_mfma_f32_16x16x32_bf16 v[74:77], v[146:149], v[224:227], v[74:77]
	v_mfma_f32_16x16x32_bf16 v[66:69], v[154:157], v[224:227], v[66:69]
	v_mfma_f32_16x16x32_bf16 v[126:129], v[162:165], v[178:181], v[126:129]
	v_mfma_f32_16x16x32_bf16 v[118:121], v[170:173], v[178:181], v[118:121]
	v_mfma_f32_16x16x32_bf16 v[110:113], v[162:165], v[186:189], v[110:113]
	v_mfma_f32_16x16x32_bf16 v[102:105], v[170:173], v[186:189], v[102:105]
	v_mfma_f32_16x16x32_bf16 v[94:97], v[162:165], v[212:215], v[94:97]
	v_mfma_f32_16x16x32_bf16 v[86:89], v[170:173], v[212:215], v[86:89]
	v_mfma_f32_16x16x32_bf16 v[78:81], v[162:165], v[220:223], v[78:81]
	v_mfma_f32_16x16x32_bf16 v[70:73], v[170:173], v[220:223], v[70:73]
	v_mfma_f32_16x16x32_bf16 v[126:129], v[166:169], v[182:185], v[126:129]
	v_mfma_f32_16x16x32_bf16 v[118:121], v[174:177], v[182:185], v[118:121]
	v_mfma_f32_16x16x32_bf16 v[110:113], v[166:169], v[208:211], v[110:113]
	v_mfma_f32_16x16x32_bf16 v[102:105], v[174:177], v[208:211], v[102:105]
	v_mfma_f32_16x16x32_bf16 v[94:97], v[166:169], v[216:219], v[94:97]
	v_mfma_f32_16x16x32_bf16 v[86:89], v[174:177], v[216:219], v[86:89]
	v_mfma_f32_16x16x32_bf16 v[78:81], v[166:169], v[224:227], v[78:81]
	v_mfma_f32_16x16x32_bf16 v[70:73], v[174:177], v[224:227], v[70:73]
	s_barrier
	s_add_i32 s9, s9, s12
	s_mov_b32 m0, s9
	s_add_u32 s20, s38, 0x80
	s_addc_u32 s21, s39, 0
	ds_read_b128 v[178:181], v161 offset:49152
	ds_read_b128 v[182:185], v161 offset:50176
	ds_read_b128 v[186:189], v161 offset:51200
	ds_read_b128 v[208:211], v161 offset:52224
	ds_read_b128 v[212:215], v161 offset:53248
	ds_read_b128 v[216:219], v161 offset:54272
	ds_read_b128 v[220:223], v161 offset:55296
	ds_read_b128 v[224:227], v161 offset:56320
	global_load_lds_dwordx4 v0, s[20:21]
	s_add_i32 m0, s9, 0x2000
	s_add_i32 s9, s74, s12
	global_load_lds_dwordx4 v130, s[20:21]
	s_add_u32 s20, s20, 0x40000
	s_addc_u32 s21, s21, 0
	s_mov_b32 m0, s9
	s_nop 0
	global_load_lds_dwordx4 v0, s[20:21]
	s_add_i32 m0, s9, 0x2000
	s_nop 0
	global_load_lds_dwordx4 v130, s[20:21]
	s_add_u32 s20, s84, 0x80
	s_addc_u32 s21, s85, 0
	s_mov_b32 m0, s78
	s_nop 0
	global_load_lds_dwordx4 v134, s[20:21]
	s_mov_b32 m0, s80
	s_nop 0
	global_load_lds_dwordx4 v132, s[20:21]
	s_waitcnt vmcnt(8)
	s_waitcnt lgkmcnt(0)
	s_barrier
	s_waitcnt lgkmcnt(0)
	v_mfma_f32_16x16x32_bf16 v[58:61], v[142:145], v[178:181], v[58:61]
	v_mfma_f32_16x16x32_bf16 v[50:53], v[150:153], v[178:181], v[50:53]
	v_mfma_f32_16x16x32_bf16 v[42:45], v[142:145], v[186:189], v[42:45]
	v_mfma_f32_16x16x32_bf16 v[34:37], v[150:153], v[186:189], v[34:37]
	v_mfma_f32_16x16x32_bf16 v[26:29], v[142:145], v[212:215], v[26:29]
	v_mfma_f32_16x16x32_bf16 v[18:21], v[150:153], v[212:215], v[18:21]
	v_mfma_f32_16x16x32_bf16 v[10:13], v[142:145], v[220:223], v[10:13]
	v_mfma_f32_16x16x32_bf16 v[2:5], v[150:153], v[220:223], v[2:5]
	v_mfma_f32_16x16x32_bf16 v[58:61], v[146:149], v[182:185], v[58:61]
	v_mfma_f32_16x16x32_bf16 v[50:53], v[154:157], v[182:185], v[50:53]
	v_mfma_f32_16x16x32_bf16 v[42:45], v[146:149], v[208:211], v[42:45]
	v_mfma_f32_16x16x32_bf16 v[34:37], v[154:157], v[208:211], v[34:37]
	v_mfma_f32_16x16x32_bf16 v[26:29], v[146:149], v[216:219], v[26:29]
	v_mfma_f32_16x16x32_bf16 v[18:21], v[154:157], v[216:219], v[18:21]
	v_mfma_f32_16x16x32_bf16 v[10:13], v[146:149], v[224:227], v[10:13]
	v_mfma_f32_16x16x32_bf16 v[2:5], v[154:157], v[224:227], v[2:5]
	v_mfma_f32_16x16x32_bf16 v[62:65], v[162:165], v[178:181], v[62:65]
	v_mfma_f32_16x16x32_bf16 v[54:57], v[170:173], v[178:181], v[54:57]
	v_mfma_f32_16x16x32_bf16 v[46:49], v[162:165], v[186:189], v[46:49]
	v_mfma_f32_16x16x32_bf16 v[38:41], v[170:173], v[186:189], v[38:41]
	v_mfma_f32_16x16x32_bf16 v[30:33], v[162:165], v[212:215], v[30:33]
	v_mfma_f32_16x16x32_bf16 v[22:25], v[170:173], v[212:215], v[22:25]
	v_mfma_f32_16x16x32_bf16 v[14:17], v[162:165], v[220:223], v[14:17]
	v_mfma_f32_16x16x32_bf16 v[6:9], v[170:173], v[220:223], v[6:9]
	v_mfma_f32_16x16x32_bf16 v[62:65], v[166:169], v[182:185], v[62:65]
	v_mfma_f32_16x16x32_bf16 v[54:57], v[174:177], v[182:185], v[54:57]
	v_mfma_f32_16x16x32_bf16 v[46:49], v[166:169], v[208:211], v[46:49]
	v_mfma_f32_16x16x32_bf16 v[38:41], v[174:177], v[208:211], v[38:41]
	v_mfma_f32_16x16x32_bf16 v[30:33], v[166:169], v[216:219], v[30:33]
	v_mfma_f32_16x16x32_bf16 v[22:25], v[174:177], v[216:219], v[22:25]
	v_mfma_f32_16x16x32_bf16 v[14:17], v[166:169], v[224:227], v[14:17]
	v_mfma_f32_16x16x32_bf16 v[6:9], v[174:177], v[224:227], v[6:9]
	s_barrier
	s_add_u32 s0, s0, 0x100
	s_addc_u32 s1, s1, 0
	s_add_u32 vcc_hi, vcc_hi, 0x100
	s_addc_u32 s8, s8, 0
	s_cmp_ge_i32 s96, s57
	s_mov_b32 s9, s96
	s_cbranch_scc0 .LBB0_222
	v_readfirstlane_b32 s96, v193
	s_bitcmp1_b32 s96, 8
	s_cbranch_scc1 .Lep_lo_222
	s_setprio 1
	s_branch .Lep_done_222

; #define PG8_BAR __builtin_amdgcn_s_barrier()
; template <class Epi, class Sched>
; __device__ __forceinline__ void gemm_phase(LAS unsigned char* lds, const Gemm g, const Sched& S, const Epi& E) {
;     ...
;         if (wr == 0) PG8_BAR;
;         { int fr_ = fr, fq_ = fq; asm volatile("" : "+v"(fr_), "+v"(fq_));
.Lep_done_222:
	v_readlane_b32 s96, v250, 43
	s_mov_b64 s[74:75], s[22:23]
